# P6: second GEMM's first k-tile loads issued before the first GEMM's last compute segment (AGPR landing), prologue only waits and writes LDS
# baseline (speedup 1.0000x reference)
; #define GM_LOAD(kt_) { GM_LOAD1(kt_, 0) GM_LOAD1(kt_, 1) GM_LOAD1(kt_, 2) GM_LOAD1(kt_, 3) GM_LOAD1(kt_, 4) GM_LOAD1(kt_, 5) GM_LOAD1(kt_, 6) GM_LOAD1(kt_, 7) }
;   __device__ __forceinline__ uint4 cvt(const Raw& r, int row, int k) const {
;     uint4 o; o.x = pack2(r.a.x, r.a.y); o.y = pack2(r.a.z, r.a.w); o.z = pack2(r.b.x, r.b.y); o.w = pack2(r.b.z, r.b.w); return o;
;   }
; template <class AL>
; __device__ __forceinline__ void gemm_mainloop(f32x16 (&acc)[2][2], const AL& al, const u16* __restrict__ Bt, int ldb, int K, char* smem) {
;     ...
;   __syncthreads();
;   GM_LOAD(0)
;   GM_STORE(0, 0)
;   __syncthreads();
.LBB0_1582:
	s_lshl_b32 s12, s37, 7
	s_lshl_b32 s0, s18, 11
	s_and_b32 s38, s12, 0x380
	s_and_b32 s0, s0, 0x1c0000
	s_lshl_b32 s12, s38, 9
	s_add_u32 s12, s14, s12
	v_accvgpr_read_b32 v0, a68
	s_addc_u32 s13, s15, 0
	v_accvgpr_read_b32 v1, a69
	v_lshl_add_u64 v[0:1], s[10:11], 0, v[0:1]
	v_lshl_add_u64 v[8:9], s[12:13], 0, v[168:169]
	v_lshl_add_u64 v[12:13], s[10:11], 0, v[128:129]
	v_lshl_add_u64 v[96:97], v[0:1], 0, v[166:167]
	v_lshl_add_u64 v[98:99], v[8:9], 0, v[170:171]
	v_lshl_add_u64 v[100:101], v[12:13], 0, v[166:167]
	v_lshl_add_u64 v[20:21], s[12:13], 0, v[172:173]
	v_lshl_add_u64 v[24:25], s[10:11], 0, v[160:161]
	v_lshl_add_u64 v[32:33], s[10:11], 0, v[136:137]
	v_lshl_add_u64 v[40:41], s[12:13], 0, v[174:175]
	v_lshl_add_u64 v[44:45], s[12:13], 0, v[180:181]
	v_lshl_add_u64 v[48:49], s[10:11], 0, v[138:139]
	s_barrier
	s_waitcnt lgkmcnt(0)
	global_load_dwordx4 v[0:3], v[96:97], off offset:16
	global_load_dwordx4 v[4:7], v[96:97], off
	global_load_dwordx4 v[8:11], v[98:99], off
	global_load_dwordx4 v[12:15], v[100:101], off offset:16
	global_load_dwordx4 v[16:19], v[100:101], off
	v_lshl_add_u64 v[102:103], v[20:21], 0, v[170:171]
	v_lshl_add_u64 v[104:105], v[24:25], 0, v[166:167]
	v_lshl_add_u64 v[106:107], v[32:33], 0, v[166:167]
	v_lshl_add_u64 v[108:109], v[40:41], 0, v[170:171]
	v_lshl_add_u64 v[110:111], v[44:45], 0, v[170:171]
	v_lshl_add_u64 v[112:113], v[48:49], 0, v[166:167]
	v_lshl_add_u64 v[56:57], s[12:13], 0, v[182:183]
	v_lshl_add_u64 v[60:61], s[10:11], 0, v[140:141]
	global_load_dwordx4 v[20:23], v[102:103], off
	global_load_dwordx4 v[24:27], v[104:105], off offset:16
	global_load_dwordx4 v[28:31], v[104:105], off
	global_load_dwordx4 v[32:35], v[106:107], off offset:16
	global_load_dwordx4 v[36:39], v[106:107], off
	global_load_dwordx4 v[40:43], v[108:109], off
	global_load_dwordx4 v[44:47], v[110:111], off
	global_load_dwordx4 v[48:51], v[112:113], off offset:16
	global_load_dwordx4 v[52:55], v[112:113], off
	v_lshl_add_u64 v[114:115], v[56:57], 0, v[170:171]
	v_lshl_add_u64 v[116:117], v[60:61], 0, v[166:167]
	v_lshl_add_u64 v[68:69], s[12:13], 0, v[184:185]
	v_lshl_add_u64 v[72:73], s[10:11], 0, v[142:143]
	global_load_dwordx4 v[56:59], v[114:115], off
	global_load_dwordx4 v[60:63], v[116:117], off offset:16
	global_load_dwordx4 v[64:67], v[116:117], off
	v_lshl_add_u64 v[118:119], v[68:69], 0, v[170:171]
	v_lshl_add_u64 v[120:121], v[72:73], 0, v[166:167]
	v_lshl_add_u64 v[80:81], s[12:13], 0, v[186:187]
	v_lshl_add_u64 v[84:85], s[10:11], 0, v[144:145]
	global_load_dwordx4 v[68:71], v[118:119], off
	global_load_dwordx4 v[72:75], v[120:121], off offset:16
	global_load_dwordx4 v[76:79], v[120:121], off
	v_lshl_add_u64 v[122:123], v[80:81], 0, v[170:171]
	v_lshl_add_u64 v[124:125], v[84:85], 0, v[166:167]
	global_load_dwordx4 v[80:83], v[122:123], off
	global_load_dwordx4 v[84:87], v[124:125], off
	global_load_dwordx4 v[88:91], v[124:125], off offset:16
	v_lshl_add_u64 v[92:93], s[12:13], 0, v[188:189]
	v_lshl_add_u64 v[126:127], v[92:93], 0, v[170:171]
	global_load_dwordx4 v[92:95], v[126:127], off
	v_accvgpr_write_b32 a84, v135
	v_lshl_add_u64 v[206:207], v[164:165], 0, s[0:1]
	s_waitcnt vmcnt(22)
	v_cvt_pk_bf16_f32 v4, v4, v5
	v_cvt_pk_bf16_f32 v5, v6, v7
	v_cvt_pk_bf16_f32 v6, v0, v1
	v_cvt_pk_bf16_f32 v7, v2, v3
	s_waitcnt vmcnt(19)
	v_cvt_pk_bf16_f32 v0, v16, v17
	v_cvt_pk_bf16_f32 v1, v18, v19
	v_cvt_pk_bf16_f32 v2, v12, v13
	v_cvt_pk_bf16_f32 v3, v14, v15
	s_waitcnt vmcnt(17)
	v_cvt_pk_bf16_f32 v14, v24, v25
	s_waitcnt vmcnt(16)
	v_cvt_pk_bf16_f32 v12, v28, v29
	v_cvt_pk_bf16_f32 v13, v30, v31
	v_cvt_pk_bf16_f32 v15, v26, v27
	s_waitcnt vmcnt(14)
	v_cvt_pk_bf16_f32 v16, v36, v37
	v_cvt_pk_bf16_f32 v17, v38, v39
	v_cvt_pk_bf16_f32 v18, v32, v33
	v_cvt_pk_bf16_f32 v19, v34, v35
	ds_write_b128 v176, v[4:7]
	ds_write_b128 v176, v[0:3] offset:4352
	ds_write_b128 v176, v[12:15] offset:8704
	ds_write_b128 v177, v[8:11]
	ds_write_b128 v178, v[20:23]
	s_waitcnt vmcnt(13)
	ds_write_b128 v179, v[40:43]
	ds_write_b128 v176, v[16:19] offset:13056
	s_waitcnt vmcnt(12)
	ds_write_b128 v210, v[44:47]
	s_waitcnt vmcnt(10)
	v_cvt_pk_bf16_f32 v0, v52, v53
	v_cvt_pk_bf16_f32 v1, v54, v55
	v_cvt_pk_bf16_f32 v2, v48, v49
	v_cvt_pk_bf16_f32 v3, v50, v51
	ds_write_b128 v176, v[0:3] offset:17408
	s_waitcnt vmcnt(9)
	ds_write_b128 v211, v[56:59]
	s_waitcnt vmcnt(7)
	v_cvt_pk_bf16_f32 v0, v64, v65
	v_cvt_pk_bf16_f32 v1, v66, v67
	v_cvt_pk_bf16_f32 v2, v60, v61
	v_cvt_pk_bf16_f32 v3, v62, v63
	ds_write_b128 v176, v[0:3] offset:21760
	s_waitcnt vmcnt(6)
	ds_write_b128 v212, v[68:71]
	s_waitcnt vmcnt(4)
	v_cvt_pk_bf16_f32 v0, v76, v77
	v_cvt_pk_bf16_f32 v1, v78, v79
	v_cvt_pk_bf16_f32 v2, v72, v73
	v_cvt_pk_bf16_f32 v3, v74, v75
	ds_write_b128 v176, v[0:3] offset:26112
	s_waitcnt vmcnt(3)
	ds_write_b128 v213, v[80:83]
	s_waitcnt vmcnt(2)
	v_cvt_pk_bf16_f32 v0, v84, v85
	v_cvt_pk_bf16_f32 v1, v86, v87
	s_waitcnt vmcnt(1)
	v_cvt_pk_bf16_f32 v2, v88, v89
	v_cvt_pk_bf16_f32 v3, v90, v91
	ds_write_b128 v176, v[0:3] offset:30464
	s_waitcnt vmcnt(0)
	ds_write_b128 v214, v[92:95]
	s_waitcnt lgkmcnt(0)
	s_barrier
; #define GM_LOAD(kt_) { GM_LOAD1(kt_, 0) GM_LOAD1(kt_, 1) GM_LOAD1(kt_, 2) GM_LOAD1(kt_, 3) GM_LOAD1(kt_, 4) GM_LOAD1(kt_, 5) GM_LOAD1(kt_, 6) GM_LOAD1(kt_, 7) }
; template <class AL>
; __device__ __forceinline__ void gemm_mainloop(f32x16 (&acc)[2][2], const AL& al, const u16* __restrict__ Bt, int ldb, int K, char* smem) {
;     ...
;   for (int kt = 0; kt < KT; kt += 2) {
;     if (kt + 1 < KT) { GM_LOAD(kt + 1) }
;     GM_COMPUTE(0)
;     if (kt + 1 < KT) { GM_STORE(kt + 1, 1) }
;     __syncthreads();
	global_load_dwordx4 v[0:3], v[98:99], off offset:256
	global_load_dwordx4 v[4:7], v[102:103], off offset:256
	global_load_dwordx4 v[8:11], v[108:109], off offset:256
	global_load_dwordx4 v[12:15], v[110:111], off offset:256
	global_load_dwordx4 v[16:19], v[114:115], off offset:256
	global_load_dwordx4 v[20:23], v[118:119], off offset:256
	global_load_dwordx4 v[24:27], v[122:123], off offset:256
	global_load_dwordx4 v[28:31], v[126:127], off offset:256
	global_load_dwordx4 v[32:35], v[96:97], off offset:528
	global_load_dwordx4 v[36:39], v[96:97], off offset:512
	global_load_dwordx4 v[40:43], v[100:101], off offset:528
	global_load_dwordx4 v[44:47], v[100:101], off offset:512
	global_load_dwordx4 v[48:51], v[104:105], off offset:528
	global_load_dwordx4 v[52:55], v[104:105], off offset:512
	global_load_dwordx4 v[56:59], v[106:107], off offset:528
	global_load_dwordx4 v[60:63], v[106:107], off offset:512
	global_load_dwordx4 v[64:67], v[112:113], off offset:528
	global_load_dwordx4 v[68:71], v[112:113], off offset:512
	global_load_dwordx4 v[72:75], v[116:117], off offset:528
	global_load_dwordx4 v[76:79], v[116:117], off offset:512
	global_load_dwordx4 v[80:83], v[120:121], off offset:528
	global_load_dwordx4 v[84:87], v[120:121], off offset:512
	global_load_dwordx4 v[88:91], v[124:125], off offset:528
	global_load_dwordx4 v[92:95], v[124:125], off offset:512
	ds_read_b128 v[96:99], v218
	ds_read_b128 v[100:103], v219
	ds_read_b128 v[104:107], v216
	ds_read_b128 v[108:111], v216 offset:32
	ds_read_b128 v[112:115], v216 offset:8704
	ds_read_b128 v[116:119], v216 offset:8736
	ds_read_b128 v[120:123], v220 offset:32
	ds_read_b128 v[124:127], v220 offset:8736
	s_waitcnt lgkmcnt(5)
	v_mfma_f32_32x32x16_bf16 a[16:31], v[104:107], v[96:99], 0
	s_mov_b32 s0, 0
	v_mfma_f32_32x32x16_bf16 a[32:47], v[104:107], v[100:103], 0
	s_waitcnt lgkmcnt(3)
	v_mfma_f32_32x32x16_bf16 a[48:63], v[112:115], v[96:99], 0
	v_mfma_f32_32x32x16_bf16 a[0:15], v[112:115], v[100:103], 0
	ds_read_b128 v[96:99], v220 offset:8768
	ds_read_b128 v[100:103], v220 offset:64
	ds_read_b128 v[104:107], v216 offset:8768
	ds_read_b128 v[112:115], v216 offset:64
	s_waitcnt lgkmcnt(5)
	v_mfma_f32_32x32x16_bf16 a[16:31], v[108:111], v[120:123], a[16:31]
	s_waitcnt lgkmcnt(4)
	v_mfma_f32_32x32x16_bf16 a[32:47], v[108:111], v[124:127], a[32:47]
	v_mfma_f32_32x32x16_bf16 a[48:63], v[116:119], v[120:123], a[48:63]
	v_mfma_f32_32x32x16_bf16 a[0:15], v[116:119], v[124:127], a[0:15]
	ds_read_b128 v[108:111], v216 offset:96
	ds_read_b128 v[116:119], v216 offset:8800
	ds_read_b128 v[120:123], v220 offset:96
	ds_read_b128 v[124:127], v220 offset:8800
	s_waitcnt lgkmcnt(4)
	v_mfma_f32_32x32x16_bf16 a[16:31], v[112:115], v[100:103], a[16:31]
	v_mfma_f32_32x32x16_bf16 a[32:47], v[112:115], v[96:99], a[32:47]
	v_mfma_f32_32x32x16_bf16 a[48:63], v[104:107], v[100:103], a[48:63]
	v_mfma_f32_32x32x16_bf16 a[0:15], v[104:107], v[96:99], a[0:15]
	ds_read_b128 v[96:99], v220 offset:8832
	ds_read_b128 v[100:103], v220 offset:128
	ds_read_b128 v[104:107], v216 offset:8832
	ds_read_b128 v[112:115], v216 offset:128
	s_waitcnt lgkmcnt(5)
	v_mfma_f32_32x32x16_bf16 a[16:31], v[108:111], v[120:123], a[16:31]
	s_waitcnt lgkmcnt(4)
	v_mfma_f32_32x32x16_bf16 a[32:47], v[108:111], v[124:127], a[32:47]
	v_mfma_f32_32x32x16_bf16 a[48:63], v[116:119], v[120:123], a[48:63]
	v_mfma_f32_32x32x16_bf16 a[0:15], v[116:119], v[124:127], a[0:15]
	ds_read_b128 v[108:111], v216 offset:160
	ds_read_b128 v[116:119], v216 offset:8864
	ds_read_b128 v[120:123], v220 offset:160
	ds_read_b128 v[124:127], v220 offset:8864
	s_waitcnt lgkmcnt(4)
	v_mfma_f32_32x32x16_bf16 a[16:31], v[112:115], v[100:103], a[16:31]
	v_mfma_f32_32x32x16_bf16 a[32:47], v[112:115], v[96:99], a[32:47]
	v_mfma_f32_32x32x16_bf16 a[48:63], v[104:107], v[100:103], a[48:63]
	v_mfma_f32_32x32x16_bf16 a[0:15], v[104:107], v[96:99], a[0:15]
	ds_read_b128 v[96:99], v220 offset:8896
	ds_read_b128 v[100:103], v220 offset:192
	ds_read_b128 v[104:107], v216 offset:8896
	ds_read_b128 v[112:115], v216 offset:192
	s_waitcnt lgkmcnt(5)
	v_mfma_f32_32x32x16_bf16 a[16:31], v[108:111], v[120:123], a[16:31]
	s_waitcnt lgkmcnt(4)
	v_mfma_f32_32x32x16_bf16 a[32:47], v[108:111], v[124:127], a[32:47]
	v_mfma_f32_32x32x16_bf16 a[48:63], v[116:119], v[120:123], a[48:63]
	v_mfma_f32_32x32x16_bf16 a[0:15], v[116:119], v[124:127], a[0:15]
	ds_read_b128 v[108:111], v216 offset:224
	ds_read_b128 v[116:119], v216 offset:8928
	ds_read_b128 v[120:123], v220 offset:224
	ds_read_b128 v[124:127], v220 offset:8928
	s_waitcnt lgkmcnt(4)
	v_mfma_f32_32x32x16_bf16 a[16:31], v[112:115], v[100:103], a[16:31]
	v_mfma_f32_32x32x16_bf16 a[32:47], v[112:115], v[96:99], a[32:47]
	v_mfma_f32_32x32x16_bf16 a[48:63], v[104:107], v[100:103], a[48:63]
	v_mfma_f32_32x32x16_bf16 a[0:15], v[104:107], v[96:99], a[0:15]
	s_waitcnt lgkmcnt(1)
	v_mfma_f32_32x32x16_bf16 a[16:31], v[108:111], v[120:123], a[16:31]
	s_waitcnt lgkmcnt(0)
	v_mfma_f32_32x32x16_bf16 a[32:47], v[108:111], v[124:127], a[32:47]
	v_mfma_f32_32x32x16_bf16 a[48:63], v[116:119], v[120:123], a[48:63]
	v_mfma_f32_32x32x16_bf16 a[0:15], v[116:119], v[124:127], a[0:15]
	s_waitcnt vmcnt(14)
	v_cvt_pk_bf16_f32 v36, v36, v37
	v_cvt_pk_bf16_f32 v37, v38, v39
	v_cvt_pk_bf16_f32 v38, v32, v33
	v_cvt_pk_bf16_f32 v39, v34, v35
	ds_write_b128 v176, v[36:39] offset:34816
	ds_write_b128 v224, v[0:3]
	s_waitcnt vmcnt(12)
	v_cvt_pk_bf16_f32 v0, v44, v45
	v_cvt_pk_bf16_f32 v1, v46, v47
	v_cvt_pk_bf16_f32 v2, v40, v41
	v_cvt_pk_bf16_f32 v3, v42, v43
	ds_write_b128 v176, v[0:3] offset:39168
	ds_write_b128 v225, v[4:7]
	s_waitcnt vmcnt(10)
	v_cvt_pk_bf16_f32 v0, v52, v53
	v_cvt_pk_bf16_f32 v1, v54, v55
	v_cvt_pk_bf16_f32 v2, v48, v49
	v_cvt_pk_bf16_f32 v3, v50, v51
	ds_write_b128 v176, v[0:3] offset:43520
	ds_write_b128 v226, v[8:11]
	s_waitcnt vmcnt(8)
	v_cvt_pk_bf16_f32 v0, v60, v61
	v_cvt_pk_bf16_f32 v1, v62, v63
	v_cvt_pk_bf16_f32 v2, v56, v57
	v_cvt_pk_bf16_f32 v3, v58, v59
	ds_write_b128 v176, v[0:3] offset:47872
	ds_write_b128 v227, v[12:15]
	s_waitcnt vmcnt(6)
	v_cvt_pk_bf16_f32 v0, v68, v69
	v_cvt_pk_bf16_f32 v1, v70, v71
	v_cvt_pk_bf16_f32 v2, v64, v65
	v_cvt_pk_bf16_f32 v3, v66, v67
	ds_write_b128 v176, v[0:3] offset:52224
	ds_write_b128 v228, v[16:19]
	s_waitcnt vmcnt(4)
	v_cvt_pk_bf16_f32 v0, v76, v77
	v_cvt_pk_bf16_f32 v1, v78, v79
	v_cvt_pk_bf16_f32 v2, v72, v73
	v_cvt_pk_bf16_f32 v3, v74, v75
	ds_write_b128 v176, v[0:3] offset:56576
	ds_write_b128 v229, v[20:23]
	s_waitcnt vmcnt(2)
	v_cvt_pk_bf16_f32 v0, v84, v85
	v_cvt_pk_bf16_f32 v1, v86, v87
	v_cvt_pk_bf16_f32 v2, v80, v81
	v_cvt_pk_bf16_f32 v3, v82, v83
	ds_write_b128 v176, v[0:3] offset:60928
	ds_write_b128 v230, v[24:27]
	s_waitcnt vmcnt(0)
	v_cvt_pk_bf16_f32 v0, v92, v93
	v_cvt_pk_bf16_f32 v1, v94, v95
	v_cvt_pk_bf16_f32 v2, v88, v89
	v_cvt_pk_bf16_f32 v3, v90, v91
	ds_write_b128 v176, v[0:3] offset:65280
	ds_write_b128 v221, v[28:31]
	s_waitcnt lgkmcnt(0)
	s_barrier
; #define GM_LOAD(kt_) { GM_LOAD1(kt_, 0) GM_LOAD1(kt_, 1) GM_LOAD1(kt_, 2) GM_LOAD1(kt_, 3) GM_LOAD1(kt_, 4) GM_LOAD1(kt_, 5) GM_LOAD1(kt_, 6) GM_LOAD1(kt_, 7) }
; template <class AL>
; __device__ __forceinline__ void gemm_mainloop(f32x16 (&acc)[2][2], const AL& al, const u16* __restrict__ Bt, int ldb, int K, char* smem) {
;     ...
;   GM_LOAD(0)
;   GM_STORE(0, 0)
;   __syncthreads();
; #pragma unroll 1
;   for (int kt = 0; kt < KT; kt += 2) {
;     if (kt + 1 < KT) { GM_LOAD(kt + 1) }
;     GM_COMPUTE(0)
;     if (kt + 1 < KT) { GM_STORE(kt + 1, 1) }
;     __syncthreads();
;     if (kt + 1 < KT) {
;       if (kt + 2 < KT) { GM_LOAD(kt + 2) }
;       GM_COMPUTE(1)
; __device__ __forceinline__ void phase6(const Params& p, char* smem) {
;     ...
;     LoadBf16 al{H3 + (size_t)m0 * 1024, 1024};
;     gemm_mainloop(acc1, al, (const u16*)(ws + OFF_WT_PG) + (size_t)n0 * 1024, 1024, 1024, smem);
	s_lshl_b64 s[10:11], s[8:9], 11
	s_add_u32 s12, s2, s10
	s_addc_u32 s13, s3, s11
	s_lshl_b32 s9, s38, 11
	v_accvgpr_read_b32 v66, a70
	s_add_u32 s40, s16, s9
	v_accvgpr_read_b32 v67, a71
	s_addc_u32 s41, s17, 0
	v_lshl_add_u64 v[66:67], s[12:13], 0, v[66:67]
	v_lshl_add_u64 v[76:77], v[66:67], 0, v[170:171]
	v_lshl_add_u64 v[66:67], s[40:41], 0, v[192:193]
	v_lshl_add_u64 v[72:73], v[66:67], 0, v[170:171]
	v_accvgpr_read_b32 v66, a72
	v_accvgpr_read_b32 v67, a73
	v_lshl_add_u64 v[66:67], s[12:13], 0, v[66:67]
	v_lshl_add_u64 v[84:85], v[66:67], 0, v[170:171]
	v_lshl_add_u64 v[66:67], s[40:41], 0, v[194:195]
	v_lshl_add_u64 v[80:81], v[66:67], 0, v[170:171]
	v_accvgpr_read_b32 v66, a74
	v_accvgpr_read_b32 v67, a75
	v_lshl_add_u64 v[66:67], s[12:13], 0, v[66:67]
	v_lshl_add_u64 v[92:93], v[66:67], 0, v[170:171]
	v_lshl_add_u64 v[66:67], s[40:41], 0, v[196:197]
	v_lshl_add_u64 v[88:89], v[66:67], 0, v[170:171]
	v_accvgpr_read_b32 v66, a76
	v_accvgpr_read_b32 v67, a77
	v_lshl_add_u64 v[66:67], s[12:13], 0, v[66:67]
	v_lshl_add_u64 v[100:101], v[66:67], 0, v[170:171]
	v_lshl_add_u64 v[66:67], s[40:41], 0, v[198:199]
	v_lshl_add_u64 v[96:97], v[66:67], 0, v[170:171]
	v_accvgpr_read_b32 v66, a78
	v_accvgpr_read_b32 v67, a79
	v_lshl_add_u64 v[66:67], s[12:13], 0, v[66:67]
	v_lshl_add_u64 v[108:109], v[66:67], 0, v[170:171]
	v_lshl_add_u64 v[66:67], s[40:41], 0, v[200:201]
	v_lshl_add_u64 v[104:105], v[66:67], 0, v[170:171]
	v_accvgpr_read_b32 v66, a80
	v_accvgpr_read_b32 v67, a81
	v_lshl_add_u64 v[66:67], s[12:13], 0, v[66:67]
	v_lshl_add_u64 v[116:117], v[66:67], 0, v[170:171]
	v_lshl_add_u64 v[66:67], s[40:41], 0, v[202:203]
	v_lshl_add_u64 v[112:113], v[66:67], 0, v[170:171]
	v_accvgpr_read_b32 v66, a82
	v_lshl_add_u64 v[64:65], s[12:13], 0, v[146:147]
	v_accvgpr_read_b32 v67, a83
	v_lshl_add_u64 v[68:69], v[64:65], 0, v[170:171]
	v_lshl_add_u64 v[64:65], s[40:41], 0, v[190:191]
	v_lshl_add_u64 v[66:67], s[12:13], 0, v[66:67]
	v_lshl_add_u64 v[122:123], s[40:41], 0, v[204:205]
	v_lshl_add_u64 v[64:65], v[64:65], 0, v[170:171]
	v_lshl_add_u64 v[120:121], v[66:67], 0, v[170:171]
	v_lshl_add_u64 v[124:125], v[122:123], 0, v[170:171]
	global_load_dwordx4 a[192:195], v[64:65], off
	global_load_dwordx4 a[196:199], v[68:69], off
	global_load_dwordx4 a[200:203], v[72:73], off
	global_load_dwordx4 a[204:207], v[76:77], off
	global_load_dwordx4 a[208:211], v[80:81], off
	global_load_dwordx4 a[212:215], v[84:85], off
	global_load_dwordx4 a[216:219], v[88:89], off
	global_load_dwordx4 a[220:223], v[92:93], off
	global_load_dwordx4 a[224:227], v[96:97], off
	global_load_dwordx4 a[228:231], v[100:101], off
	global_load_dwordx4 a[232:235], v[104:105], off
	global_load_dwordx4 a[236:239], v[108:109], off
	global_load_dwordx4 a[240:243], v[112:113], off
	global_load_dwordx4 a[244:247], v[116:117], off
	global_load_dwordx4 a[248:251], v[120:121], off
	global_load_dwordx4 a[252:255], v[124:125], off
	ds_read_b128 v[0:3], v216 offset:34816
	ds_read_b128 v[4:7], v216 offset:34848
	ds_read_b128 v[8:11], v216 offset:43520
	ds_read_b128 v[12:15], v216 offset:43552
	ds_read_b128 v[16:19], v222
	ds_read_b128 v[20:23], v223 offset:32
	ds_read_b128 v[24:27], v231
	ds_read_b128 v[28:31], v223 offset:8736
	s_waitcnt lgkmcnt(1)
	v_mfma_f32_32x32x16_bf16 a[16:31], v[0:3], v[24:27], a[16:31]
	v_mfma_f32_32x32x16_bf16 a[32:47], v[0:3], v[16:19], a[32:47]
	v_mfma_f32_32x32x16_bf16 a[48:63], v[8:11], v[24:27], a[48:63]
	v_mfma_f32_32x32x16_bf16 a[0:15], v[8:11], v[16:19], a[0:15]
	ds_read_b128 v[0:3], v223 offset:8768
	ds_read_b128 v[8:11], v223 offset:64
	ds_read_b128 v[16:19], v216 offset:43584
	ds_read_b128 v[24:27], v216 offset:34880
	v_mfma_f32_32x32x16_bf16 a[16:31], v[4:7], v[20:23], a[16:31]
	s_waitcnt lgkmcnt(4)
	v_mfma_f32_32x32x16_bf16 a[32:47], v[4:7], v[28:31], a[32:47]
	v_mfma_f32_32x32x16_bf16 a[48:63], v[12:15], v[20:23], a[48:63]
	v_mfma_f32_32x32x16_bf16 a[0:15], v[12:15], v[28:31], a[0:15]
	ds_read_b128 v[4:7], v216 offset:34912
	ds_read_b128 v[12:15], v216 offset:43616
	ds_read_b128 v[20:23], v223 offset:96
	ds_read_b128 v[28:31], v223 offset:8800
	s_waitcnt lgkmcnt(4)
	v_mfma_f32_32x32x16_bf16 a[16:31], v[24:27], v[8:11], a[16:31]
	v_mfma_f32_32x32x16_bf16 a[32:47], v[24:27], v[0:3], a[32:47]
	v_mfma_f32_32x32x16_bf16 a[48:63], v[16:19], v[8:11], a[48:63]
	v_mfma_f32_32x32x16_bf16 a[0:15], v[16:19], v[0:3], a[0:15]
	ds_read_b128 v[0:3], v223 offset:8832
	ds_read_b128 v[8:11], v223 offset:128
	ds_read_b128 v[16:19], v216 offset:43648
	ds_read_b128 v[24:27], v216 offset:34944
	s_waitcnt lgkmcnt(5)
	v_mfma_f32_32x32x16_bf16 a[16:31], v[4:7], v[20:23], a[16:31]
	s_waitcnt lgkmcnt(4)
	v_mfma_f32_32x32x16_bf16 a[32:47], v[4:7], v[28:31], a[32:47]
	v_mfma_f32_32x32x16_bf16 a[48:63], v[12:15], v[20:23], a[48:63]
	v_mfma_f32_32x32x16_bf16 a[0:15], v[12:15], v[28:31], a[0:15]
	ds_read_b128 v[4:7], v216 offset:34976
	ds_read_b128 v[12:15], v216 offset:43680
	ds_read_b128 v[20:23], v223 offset:160
	ds_read_b128 v[28:31], v223 offset:8864
	s_waitcnt lgkmcnt(4)
	v_mfma_f32_32x32x16_bf16 a[16:31], v[24:27], v[8:11], a[16:31]
	v_mfma_f32_32x32x16_bf16 a[32:47], v[24:27], v[0:3], a[32:47]
	v_mfma_f32_32x32x16_bf16 a[48:63], v[16:19], v[8:11], a[48:63]
	v_mfma_f32_32x32x16_bf16 a[0:15], v[16:19], v[0:3], a[0:15]
	ds_read_b128 v[0:3], v223 offset:8896
	ds_read_b128 v[8:11], v223 offset:192
	ds_read_b128 v[16:19], v216 offset:43712
	ds_read_b128 v[24:27], v216 offset:35008
	s_waitcnt lgkmcnt(5)
; #define GM_LOAD(kt_) { GM_LOAD1(kt_, 0) GM_LOAD1(kt_, 1) GM_LOAD1(kt_, 2) GM_LOAD1(kt_, 3) GM_LOAD1(kt_, 4) GM_LOAD1(kt_, 5) GM_LOAD1(kt_, 6) GM_LOAD1(kt_, 7) }
; template <class AL>
; __device__ __forceinline__ void gemm_mainloop(f32x16 (&acc)[2][2], const AL& al, const u16* __restrict__ Bt, int ldb, int K, char* smem) {
;     ...
;   __syncthreads();
;   GM_LOAD(0)
;   GM_STORE(0, 0)
;   __syncthreads();
; __device__ __forceinline__ void phase6(const Params& p, char* smem) {
;     ...
;     f32x16 acc1[2][2]; zero_acc(acc1);
;     unsigned pe[2][2][8];
;     {
;       LoadF32 lp{m0 < NTP ? p.p_prompt + (size_t)m0 * 256 : p.p_sample + (size_t)(m0 - NTP) * 256, 256};
;       gemm_mainloop(acc1, lp, (const u16*)(ws + OFF_WT_PLE) + (size_t)n0 * 256, 256, 256, smem);
; #pragma unroll
;       for (int i = 0; i < 2; i++)
; #pragma unroll
;         for (int j = 0; j < 2; j++)
; #pragma unroll
;           for (int e = 0; e < 8; e++) pe[i][j][e] = pack2(acc1[i][j][2 * e], acc1[i][j][2 * e + 1]);
;       zero_acc(acc1);
;     }
;     LoadBf16 al{H3 + (size_t)m0 * 1024, 1024};
;     gemm_mainloop(acc1, al, (const u16*)(ws + OFF_WT_PG) + (size_t)n0 * 1024, 1024, 1024, smem);
	v_mfma_f32_32x32x16_bf16 a[16:31], v[4:7], v[20:23], a[16:31]
	s_waitcnt lgkmcnt(4)
	v_mfma_f32_32x32x16_bf16 a[32:47], v[4:7], v[28:31], a[32:47]
	v_mfma_f32_32x32x16_bf16 a[48:63], v[12:15], v[20:23], a[48:63]
	v_mfma_f32_32x32x16_bf16 a[0:15], v[12:15], v[28:31], a[0:15]
	ds_read_b128 v[4:7], v216 offset:35040
	ds_read_b128 v[20:23], v216 offset:43744
	ds_read_b128 v[12:15], v223 offset:224
	ds_read_b128 v[28:31], v223 offset:8928
	s_waitcnt lgkmcnt(4)
	v_mfma_f32_32x32x16_bf16 a[16:31], v[24:27], v[8:11], a[16:31]
	v_mfma_f32_32x32x16_bf16 a[32:47], v[24:27], v[0:3], a[32:47]
	v_mfma_f32_32x32x16_bf16 a[48:63], v[16:19], v[8:11], a[48:63]
	v_mfma_f32_32x32x16_bf16 a[0:15], v[16:19], v[0:3], a[0:15]
	s_waitcnt lgkmcnt(1)
	v_mfma_f32_32x32x16_bf16 a[16:31], v[4:7], v[12:15], a[16:31]
	s_waitcnt lgkmcnt(0)
	v_mfma_f32_32x32x16_bf16 a[32:47], v[4:7], v[28:31], a[32:47]
	s_nop 9
	v_accvgpr_read_b32 v47, a31
	v_accvgpr_read_b32 v46, a30
	v_accvgpr_read_b32 v45, a29
	v_mfma_f32_32x32x16_bf16 a[48:63], v[20:23], v[12:15], a[48:63]
	v_accvgpr_read_b32 v44, a28
	v_accvgpr_read_b32 v43, a27
	v_accvgpr_read_b32 v42, a26
	v_accvgpr_read_b32 v41, a25
	v_accvgpr_read_b32 v63, a47
	v_accvgpr_read_b32 v40, a24
	v_accvgpr_read_b32 v39, a23
	v_mfma_f32_32x32x16_bf16 a[0:15], v[20:23], v[28:31], a[0:15]
	v_accvgpr_read_b32 v38, a22
	v_accvgpr_read_b32 v37, a21
	v_accvgpr_read_b32 v36, a20
	v_accvgpr_read_b32 v35, a19
	v_accvgpr_read_b32 v0, a48
	v_accvgpr_read_b32 v34, a18
	v_accvgpr_read_b32 v33, a17
	v_accvgpr_read_b32 v32, a16
	v_accvgpr_read_b32 v62, a46
	v_accvgpr_read_b32 v61, a45
	v_accvgpr_read_b32 v60, a44
	v_accvgpr_read_b32 v59, a43
	v_accvgpr_read_b32 v31, a15
	v_accvgpr_read_b32 v58, a42
	v_accvgpr_read_b32 v57, a41
	v_accvgpr_read_b32 v56, a40
	v_accvgpr_read_b32 v55, a39
	v_accvgpr_read_b32 v54, a38
	v_accvgpr_read_b32 v53, a37
	v_accvgpr_read_b32 v52, a36
	v_accvgpr_read_b32 v51, a35
	v_accvgpr_read_b32 v50, a34
	v_accvgpr_read_b32 v49, a33
	v_accvgpr_read_b32 v48, a32
	v_accvgpr_read_b32 v1, a49
	v_accvgpr_read_b32 v2, a50
	v_accvgpr_read_b32 v3, a51
	v_accvgpr_read_b32 v4, a52
	v_accvgpr_read_b32 v5, a53
	v_accvgpr_read_b32 v6, a54
	v_accvgpr_read_b32 v7, a55
	v_accvgpr_read_b32 v8, a56
	v_accvgpr_read_b32 v9, a57
	v_accvgpr_read_b32 v10, a58
	v_accvgpr_read_b32 v11, a59
	v_accvgpr_read_b32 v12, a60
	v_accvgpr_read_b32 v13, a61
	v_accvgpr_read_b32 v14, a62
	v_accvgpr_read_b32 v15, a63
	v_accvgpr_read_b32 v30, a14
	v_accvgpr_read_b32 v29, a13
	v_accvgpr_read_b32 v28, a12
	v_accvgpr_read_b32 v27, a11
	v_accvgpr_read_b32 v26, a10
	v_accvgpr_read_b32 v25, a9
	v_accvgpr_read_b32 v24, a8
	v_accvgpr_read_b32 v23, a7
	v_accvgpr_read_b32 v22, a6
	v_accvgpr_read_b32 v21, a5
	v_accvgpr_read_b32 v20, a4
	v_accvgpr_read_b32 v19, a3
	v_accvgpr_read_b32 v18, a2
	v_accvgpr_read_b32 v17, a1
	v_accvgpr_read_b32 v16, a0
	s_barrier
	s_barrier
	v_accvgpr_write_b32 a15, 0
	v_accvgpr_write_b32 a14, 0
	v_accvgpr_write_b32 a13, 0
	v_accvgpr_write_b32 a12, 0
	v_accvgpr_write_b32 a11, 0
	v_accvgpr_write_b32 a10, 0
	v_accvgpr_write_b32 a9, 0
	v_accvgpr_write_b32 a8, 0
	v_lshl_add_u64 v[208:209], v[164:165], 0, s[10:11]
	v_accvgpr_write_b32 a7, 0
	v_accvgpr_write_b32 a6, 0
	v_accvgpr_write_b32 a5, 0
	v_accvgpr_write_b32 a4, 0
	v_accvgpr_write_b32 a3, 0
	v_accvgpr_write_b32 a2, 0
	v_accvgpr_write_b32 a1, 0
	v_accvgpr_write_b32 a0, 0
	v_accvgpr_write_b32 a47, 0
	v_accvgpr_write_b32 a46, 0
	v_accvgpr_write_b32 a45, 0
	v_accvgpr_write_b32 a44, 0
	v_accvgpr_write_b32 a43, 0
	v_accvgpr_write_b32 a42, 0
	v_accvgpr_write_b32 a41, 0
	v_accvgpr_write_b32 a40, 0
	v_accvgpr_write_b32 a39, 0
	v_accvgpr_write_b32 a38, 0
	v_accvgpr_write_b32 a37, 0
	v_accvgpr_write_b32 a36, 0
	v_accvgpr_write_b32 a35, 0
	v_accvgpr_write_b32 a34, 0
	v_accvgpr_write_b32 a33, 0
	v_accvgpr_write_b32 a32, 0
	v_accvgpr_write_b32 a63, 0
	v_accvgpr_write_b32 a62, 0
	v_accvgpr_write_b32 a61, 0
	v_accvgpr_write_b32 a60, 0
	v_accvgpr_write_b32 a59, 0
	v_accvgpr_write_b32 a58, 0
	v_accvgpr_write_b32 a57, 0
	v_accvgpr_write_b32 a56, 0
	v_accvgpr_write_b32 a55, 0
	v_accvgpr_write_b32 a54, 0
	v_accvgpr_write_b32 a53, 0
	v_accvgpr_write_b32 a52, 0
	v_accvgpr_write_b32 a51, 0
	v_accvgpr_write_b32 a50, 0
	v_accvgpr_write_b32 a49, 0
	v_accvgpr_write_b32 a48, 0
	v_accvgpr_write_b32 a31, 0
	v_accvgpr_write_b32 a30, 0
	v_accvgpr_write_b32 a29, 0
	v_accvgpr_write_b32 a28, 0
	v_accvgpr_write_b32 a27, 0
	v_accvgpr_write_b32 a26, 0
	v_accvgpr_write_b32 a25, 0
	v_accvgpr_write_b32 a24, 0
	v_accvgpr_write_b32 a23, 0
	v_accvgpr_write_b32 a22, 0
	v_accvgpr_write_b32 a21, 0
	v_accvgpr_write_b32 a20, 0
	v_accvgpr_write_b32 a19, 0
	v_accvgpr_write_b32 a18, 0
	v_accvgpr_write_b32 a17, 0
	v_accvgpr_write_b32 a16, 0
	s_waitcnt vmcnt(0)
	ds_write_b128 v176, a[196:199]
	ds_write_b128 v177, a[192:195]
	ds_write_b128 v176, a[204:207] offset:4352
	ds_write_b128 v178, a[200:203]
	ds_write_b128 v176, a[212:215] offset:8704
	ds_write_b128 v179, a[208:211]
	ds_write_b128 v176, a[220:223] offset:13056
	ds_write_b128 v210, a[216:219]
	ds_write_b128 v176, a[228:231] offset:17408
	ds_write_b128 v211, a[224:227]
	ds_write_b128 v176, a[236:239] offset:21760
	ds_write_b128 v212, a[232:235]
	ds_write_b128 v176, a[244:247] offset:26112
	ds_write_b128 v213, a[240:243]
	ds_write_b128 v176, a[248:251] offset:30464
	ds_write_b128 v214, a[252:255]
	s_waitcnt lgkmcnt(0)
	s_barrier
	s_branch .LBB0_1584
